# GEMM tile order inside each 64-tile XCD round changed to Z-order (n bits 0,2,4 / m bits 1,3,5 of the slot index)
# speedup vs baseline: 1.0098x; 1.0022x over previous
; DI void tile_map(int t, int MT, int NT, int& mt, int& nt) {
;   const int xc = t & 7, j = t >> 3, mtx = MT >> 3, full = NT >> 3, per = mtx * 8;
;   int sc = j / per, rem, w;
;   if (sc < full) { rem = j - sc * per; w = 8; }
;   else { sc = full; rem = j - full * per; w = NT & 7; }
;   const int m = rem / w, nn = rem - m * w;
;   mt = xc * mtx + m; nt = sc * 8 + nn;
; }
; template <int EPI>
; DI void gemm_phase(const Params& p, int layer, const bf16_t* __restrict__ A, int lda, const bf16_t* __restrict__ Bt, int ldb, int K, int MT, int NT,
;                    char* smem, bool rev = false) {
;     ...
;   const int total = MT * NT;
;   int t = rev ? (int)(gridDim.x - 1 - blockIdx.x) : (int)blockIdx.x;
;   if (t >= total) return;
;   uint4 pa0, pa1, pa2, pa3, pb0, pb1, pb2, pb3, qa0, qa1, qa2, qa3, qb0, qb1, qb2, qb3;
;   const int lr = tid >> 3, lc = (tid & 7) * 8;
;   const int nk = K >> 6;
;   const int soff = lr * LDT + lc;
;   const int aoff = (wr * 64 + (lane & 31)) * LDT + (lane >> 5) * 8;
;   const int boff = (wc * 64 + (lane & 31)) * LDT + (lane >> 5) * 8;
;   int mt, nt; tile_map(t, MT, NT, mt, nt);
;   int m0 = mt * 128, n0 = nt * 128;
.Lmg_tile:
	s_cmp_ge_u32 s66, s64
	s_cbranch_scc1 .Lmg_done
	s_and_b32 s0, s66, 7
	s_lshr_b32 s1, s66, 3
	s_or_b32 s10, s1, 63
	s_lshr_b32 s11, s64, 3
	s_cmp_lt_u32 s10, s11
	s_cbranch_scc0 .Lmg_noash_10
	s_mov_b32 s10, 0
	s_bfe_u32 s11, s1, 0x10000
	s_or_b32 s10, s10, s11
	s_bfe_u32 s11, s1, 0x10002
	s_lshl_b32 s11, s11, 1
	s_or_b32 s10, s10, s11
	s_bfe_u32 s11, s1, 0x10004
	s_lshl_b32 s11, s11, 2
	s_or_b32 s10, s10, s11
	s_bfe_u32 s11, s1, 0x10001
	s_lshl_b32 s11, s11, 3
	s_or_b32 s10, s10, s11
	s_bfe_u32 s11, s1, 0x10003
	s_lshl_b32 s11, s11, 4
	s_or_b32 s10, s10, s11
	s_bfe_u32 s11, s1, 0x10005
	s_lshl_b32 s11, s11, 5
	s_or_b32 s10, s10, s11
	s_andn2_b32 s1, s1, 63
	s_or_b32 s1, s1, s10
	s_branch .Lmg_noash_10
	s_and_b32 s10, s1, 3
	s_bfe_u32 s11, s1, 0x10005
	s_lshl_b32 s11, s11, 2
	s_or_b32 s10, s10, s11
	s_bfe_u32 s11, s1, 0x30002
	s_lshl_b32 s11, s11, 3
	s_or_b32 s10, s10, s11
	s_andn2_b32 s1, s1, 63
	s_or_b32 s1, s1, s10
.Lmg_noash_10:
	s_lshr_b32 s10, s1, 3
	s_mul_i32 s10, s10, s63
	s_lshr_b32 s10, s10, 16
	s_lshr_b32 s11, s62, 3
	s_mov_b32 s12, 8
	s_mov_b32 s13, 0x2000
	s_cmp_ge_u32 s10, s11
	s_cbranch_scc0 .Lmg_tm_11
	s_mov_b32 s10, s11
	s_and_b32 s12, s62, 7
	s_mov_b32 s13, s69
